# retention scan: LDS tile layout 288*(r&7)+2320*(r>>3) so plain and transposed reads are both bank-conflict free
# speedup vs baseline: 1.0717x; 1.0717x over previous
.LBB0_1368:
	s_cmp_lt_i32 s14, 0
	s_cselect_b64 s[4:5], -1, 0
	s_and_b64 vcc, exec, s[4:5]
	s_cbranch_vccnz .LBB0_1355
	v_sub_co_u32_e64 v0, s[36:37], s14, 64
	s_xor_b64 s[6:7], s[36:37], -1
	s_and_b64 s[0:1], s[36:37], exec
	v_readfirstlane_b32 s0, v0
	s_cselect_b32 s18, s14, s0
	s_cselect_b32 s55, s48, 0x100
	s_ashr_i32 s14, s18, 4
	s_lshl_b32 s15, s14, 10
	s_bfe_u32 s1, s18, 0x30001
	s_and_b32 s0, s18, 1
	s_add_i32 s38, s15, 0x2000
	s_lshl_b32 s39, s14, 8
	s_and_b64 s[14:15], s[36:37], exec
	s_cselect_b32 s56, s38, s39
	s_lshl_b32 s15, s0, 3
	s_and_b32 s14, s18, -16
	s_or_b32 s18, s15, s1
	s_or_b32 s14, s18, s14
	s_ashr_i32 s15, s14, 31
	s_lshl_b64 s[14:15], s[14:15], 16
	s_add_u32 s38, s44, s14
	s_addc_u32 s39, s45, s15
	s_and_b64 s[36:37], s[36:37], exec
	s_cselect_b32 s43, s39, 0
	s_cselect_b32 s42, s38, 0
	s_lshl_b32 s18, s18, 2
	v_readlane_b32 s76, v254, 0
	v_mov_b32_e32 v0, s18
	v_readlane_b32 s78, v254, 2
	v_readlane_b32 s79, v254, 3
	v_mov_b32_e32 v1, v224
	v_mov_b32_e32 v127, v2
	v_mov_b32_e32 v125, v2
	v_mov_b32_e32 v123, v2
	v_mov_b32_e32 v119, v2
	global_load_dword v4, v0, s[78:79]
	v_mov_b32_e32 v117, v2
	v_bfe_u32 v3, v1, 4, 2
	v_lshlrev_b32_e32 v49, 2, v3
	s_waitcnt vmcnt(4)
	v_or_b32_e32 v9, 3, v49
	v_lshlrev_b32_e32 v10, 8, v9
	v_and_b32_e32 v10, 0xe00, v10
	v_or_b32_e32 v82, 0x4000, v10
	v_ashrrev_i32_e32 v174, 4, v1
	s_waitcnt vmcnt(3)
	v_ashrrev_i32_e32 v5, 2, v1
	v_lshlrev_b32_e32 v6, 6, v1
	v_sub_u32_e32 v7, s55, v174
	v_and_b32_e32 v0, -16, v5
	v_bfi_b32 v112, -16, v5, v1
	v_and_b32_e32 v5, 0xc00, v6
	v_add_u32_e32 v6, 32, v174
	v_subrev_u32_e32 v7, 33, v7
	v_and_b32_e32 v173, 15, v1
	v_or_b32_e32 v102, 0x7000, v5
	v_or_b32_e32 v104, 0x3200, v5
	v_or_b32_e32 v106, 0x7200, v5
	v_or_b32_e32 v116, 0xf000, v5
	v_or_b32_e32 v114, 0xb200, v5
	v_or_b32_e32 v140, 0xf200, v5
	v_or_b32_e32 v8, 2, v49
	v_lshlrev_b32_e32 v80, 8, v8
	v_lshlrev_b32_e32 v76, 10, v3
	v_ashrrev_i32_e32 v113, 31, v112
	v_or_b32_e32 v126, 0xa000, v76
	v_or_b32_e32 v124, 0xe000, v76
	v_or_b32_e32 v122, 0xa200, v76
	v_or_b32_e32 v118, 0xb000, v76
	v_mov_b32_e32 v115, v2
	v_mov_b32_e32 v141, v2
	v_mov_b32_e32 v109, v2
	v_mov_b32_e32 v111, v2
	v_or_b32_e32 v108, 0x8000, v76
	v_or_b32_e32 v110, 0xc000, v76
	v_or_b32_e32 v138, 0x8200, v76
	v_mov_b32_e32 v139, v2
	v_or_b32_e32 v134, 0x9000, v76
	v_mov_b32_e32 v135, v2
	v_or_b32_e32 v132, 0xd000, v76
	v_mov_b32_e32 v133, v2
	v_or_b32_e32 v130, 0x9200, v76
	v_mov_b32_e32 v131, v2
	v_or_b32_e32 v128, 0xd200, v76
	v_mov_b32_e32 v129, v2
	v_or_b32_e32 v120, 0xe200, v76
	v_mov_b32_e32 v121, v2
	v_mov_b32_e32 v93, v2
	v_mov_b32_e32 v95, v2
	v_mov_b32_e32 v97, v2
	v_mov_b32_e32 v101, v2
	v_mov_b32_e32 v103, v2
	v_mov_b32_e32 v105, v2
	v_mov_b32_e32 v107, v2
	v_or_b32_e32 v92, 0x2000, v76
	v_or_b32_e32 v94, 0x6000, v76
	v_or_b32_e32 v96, 0x2200, v76
	v_or_b32_e32 v100, 0x3000, v76
	v_or_b32_e32 v136, 0xc200, v76
	v_mov_b32_e32 v137, v2
	v_mov_b32_e32 v77, v2
	v_mov_b32_e32 v79, v2
	v_mov_b32_e32 v81, v2
	v_mov_b32_e32 v83, v2
	v_mov_b32_e32 v85, v2
	v_mov_b32_e32 v87, v2
	v_mov_b32_e32 v89, v2
	v_mov_b32_e32 v91, v2
	v_mov_b32_e32 v99, v2
	v_or_b32_e32 v78, 0x4000, v76
	v_or_b32_e32 v84, 0x1000, v76
	v_or_b32_e32 v86, 0x5000, v76
	v_or_b32_e32 v88, 0x1200, v76
	v_or_b32_e32 v90, 0x5200, v76
	v_or_b32_e32 v98, 0x6200, v76
	v_xor_b32_e32 v23, 28, v49
	s_waitcnt vmcnt(0)
	v_mul_f32_e64 v11, |v4|, s49
	v_exp_f32_e32 v11, v11
	v_max_f32_e32 v4, v4, v4
	v_min_f32_e32 v4, 0, v4
	v_lshlrev_b32_e32 v48, 3, v1
	v_add_f32_e32 v10, 1.0, v11
	v_cmp_gt_f32_e32 vcc, s50, v10
	s_and_b64 s[36:37], vcc, exec
	s_cselect_b32 s18, 32, 0
	s_lshl_b32 s46, s1, 8
	s_add_u32 s36, s60, s46
	v_ldexp_f32 v10, v10, s18
	s_addc_u32 s37, s61, 0
	v_log_f32_e32 v10, v10
	s_add_u32 s38, s17, s46
	s_addc_u32 s39, s19, 0
	s_add_u32 s40, s88, s46
	s_addc_u32 s41, s89, 0
	v_mul_f32_e32 v12, 0x3f317217, v10
	s_cmp_eq_u32 s0, 0
	v_cndmask_b32_e32 v11, 0, v172, vcc
	v_fma_f32 v12, v10, s51, -v12
	s_cselect_b64 vcc, -1, 0
	v_fmac_f32_e32 v12, 0x3377d1cf, v10
	s_and_b64 s[0:1], vcc, exec
	v_fmac_f32_e32 v12, 0x3f317217, v10
	v_cmp_lt_f32_e64 s[0:1], |v10|, s52
	v_cndmask_b32_e32 v22, v7, v6, vcc
	v_sub_u32_e32 v7, v173, v9
	v_cndmask_b32_e64 v6, v10, v12, s[0:1]
	v_sub_f32_e32 v6, v6, v11
	v_sub_f32_e32 v51, v4, v6
	v_sub_u32_e32 v4, v173, v49
	v_cvt_f32_u32_e32 v6, v4
	s_cselect_b32 s0, s53, 0xd522000
	s_add_u32 s0, s24, s0
	s_addc_u32 s1, s25, 0
	v_mul_f32_e32 v5, v51, v6
	v_add_u32_e32 v6, 16, v4
	v_cvt_f32_u32_e32 v6, v6
	v_mul_f32_e32 v5, 0x3fb8aa3b, v5
	s_add_u32 s46, s0, s46
	v_exp_f32_e32 v5, v5
	v_mul_f32_e32 v6, v51, v6
	s_addc_u32 s47, s1, 0
	v_cmp_lt_i32_e64 s[0:1], -1, v4
	v_xad_u32 v4, v49, -1, v173
	v_mul_f32_e32 v6, 0x3fb8aa3b, v6
	v_exp_f32_e32 v144, v6
	v_add_u32_e32 v6, 16, v4
	v_cvt_f32_u32_e32 v6, v6
	v_cndmask_b32_e64 v142, 0, v5, s[0:1]
	v_cvt_f32_u32_e32 v5, v4
	v_cmp_lt_i32_e64 s[0:1], -1, v4
	v_mul_f32_e32 v6, v51, v6
	v_sub_u32_e32 v4, v173, v8
	v_mul_f32_e32 v5, v51, v5
	v_mul_f32_e32 v6, 0x3fb8aa3b, v6
	v_mul_f32_e32 v5, 0x3fb8aa3b, v5
	v_exp_f32_e32 v145, v6
	v_add_u32_e32 v6, 16, v4
	v_exp_f32_e32 v5, v5
	v_cvt_f32_u32_e32 v6, v6
	v_cvt_f32_u32_e32 v8, v7
	s_lshr_b32 s58, s55, 5
	v_cndmask_b32_e64 v143, 0, v5, s[0:1]
	v_cvt_f32_u32_e32 v5, v4
	v_cmp_lt_i32_e64 s[0:1], -1, v4
	v_mul_f32_e32 v4, v51, v6
	v_add_u32_e32 v6, 16, v7
	v_cvt_f32_u32_e32 v6, v6
	v_mul_f32_e32 v5, v51, v5
	v_mul_f32_e32 v4, 0x3fb8aa3b, v4
	v_mul_f32_e32 v5, 0x3fb8aa3b, v5
	v_exp_f32_e32 v148, v4
	v_mul_f32_e32 v4, v51, v6
	v_exp_f32_e32 v5, v5
	v_mul_f32_e32 v4, 0x3fb8aa3b, v4
	v_exp_f32_e32 v149, v4
	v_xor_b32_e32 v4, 31, v49
	v_cvt_f32_ubyte0_e32 v4, v4
	v_mul_f32_e32 v4, v51, v4
	v_cndmask_b32_e64 v146, 0, v5, s[0:1]
	v_mul_f32_e32 v5, v51, v8
	v_mul_f32_e32 v4, 0x3fb8aa3b, v4
	v_mul_f32_e32 v5, 0x3fb8aa3b, v5
	v_exp_f32_e32 v150, v4
	v_xor_b32_e32 v4, 30, v49
	v_exp_f32_e32 v5, v5
	v_cvt_f32_ubyte0_e32 v4, v4
	v_mul_f32_e32 v4, v51, v4
	v_mul_f32_e32 v4, 0x3fb8aa3b, v4
	v_cmp_lt_i32_e64 s[0:1], -1, v7
	v_exp_f32_e32 v151, v4
	v_xor_b32_e32 v4, 29, v49
	s_cmp_eq_u64 s[42:43], 0
	v_cndmask_b32_e64 v147, 0, v5, s[0:1]
	v_cvt_f32_ubyte0_e32 v4, v4
	s_cselect_b64 s[0:1], -1, 0
	v_mul_f32_e32 v4, v51, v4
	s_and_b64 s[62:63], s[0:1], exec
	v_mul_f32_e32 v4, 0x3fb8aa3b, v4
	s_cselect_b32 s18, s45, s43
	s_cselect_b32 s42, s44, s42
	v_exp_f32_e32 v152, v4
	v_mov_b32_e32 v4, s42
	v_mov_b32_e32 v5, s18
	v_lshl_add_u64 v[4:5], v[112:113], 2, v[4:5]
	v_lshl_add_u64 v[6:7], v[4:5], 0, v[118:119]
	v_lshl_add_u64 v[8:9], v[4:5], 0, v[116:117]
	v_lshl_add_u64 v[10:11], v[4:5], 0, v[114:115]
	v_lshl_add_u64 v[12:13], v[4:5], 0, v[140:141]
	v_lshl_add_u64 v[14:15], v[4:5], 0, v[126:127]
	v_lshl_add_u64 v[16:17], v[4:5], 0, v[124:125]
	v_lshl_add_u64 v[18:19], v[4:5], 0, v[122:123]
	v_lshl_add_u64 v[20:21], v[4:5], 0, v[120:121]
	global_load_dword v24, v[6:7], off
	global_load_dword v25, v[8:9], off
	global_load_dword v26, v[10:11], off
	global_load_dword v27, v[12:13], off
	global_load_dword v28, v[14:15], off
	global_load_dword v29, v[16:17], off
	global_load_dword v30, v[18:19], off
	global_load_dword v31, v[20:21], off
	v_lshl_add_u64 v[6:7], v[4:5], 0, v[134:135]
	v_lshl_add_u64 v[8:9], v[4:5], 0, v[132:133]
	v_lshl_add_u64 v[10:11], v[4:5], 0, v[130:131]
	v_lshl_add_u64 v[12:13], v[4:5], 0, v[128:129]
	v_lshl_add_u64 v[14:15], v[4:5], 0, v[108:109]
	v_lshl_add_u64 v[16:17], v[4:5], 0, v[110:111]
	v_lshl_add_u64 v[18:19], v[4:5], 0, v[138:139]
	v_lshl_add_u64 v[20:21], v[4:5], 0, v[136:137]
	global_load_dword v32, v[6:7], off
	global_load_dword v33, v[8:9], off
	global_load_dword v34, v[10:11], off
	global_load_dword v35, v[12:13], off
	global_load_dword v36, v[14:15], off
	global_load_dword v37, v[16:17], off
	global_load_dword v38, v[18:19], off
	global_load_dword v39, v[20:21], off
	v_lshl_add_u64 v[6:7], v[4:5], 0, v[100:101]
	v_lshl_add_u64 v[8:9], v[4:5], 0, v[102:103]
	v_lshl_add_u64 v[10:11], v[4:5], 0, v[104:105]
	v_lshl_add_u64 v[12:13], v[4:5], 0, v[106:107]
	v_lshl_add_u64 v[14:15], v[4:5], 0, v[92:93]
	v_lshl_add_u64 v[16:17], v[4:5], 0, v[94:95]
	v_lshl_add_u64 v[18:19], v[4:5], 0, v[96:97]
	v_lshl_add_u64 v[20:21], v[4:5], 0, v[98:99]
	global_load_dword v40, v[6:7], off
	global_load_dword v41, v[8:9], off
	global_load_dword v42, v[10:11], off
	global_load_dword v43, v[12:13], off
	global_load_dword v44, v[14:15], off
	global_load_dword v45, v[16:17], off
	global_load_dword v46, v[18:19], off
	global_load_dword v47, v[20:21], off
	v_lshl_add_u64 v[6:7], v[4:5], 0, v[84:85]
	v_lshl_add_u64 v[8:9], v[4:5], 0, v[86:87]
	v_lshl_add_u64 v[10:11], v[4:5], 0, v[88:89]
	v_lshl_add_u64 v[12:13], v[4:5], 0, v[90:91]
	v_lshl_add_u64 v[14:15], v[4:5], 0, v[76:77]
	v_lshl_add_u64 v[16:17], v[4:5], 0, v[78:79]
	v_lshl_add_u64 v[18:19], v[4:5], 0, v[80:81]
	v_lshl_add_u64 v[4:5], v[4:5], 0, v[82:83]
	global_load_dword v52, v[6:7], off
	global_load_dword v53, v[8:9], off
	global_load_dword v54, v[10:11], off
	global_load_dword v55, v[12:13], off
	global_load_dword v56, v[14:15], off
	global_load_dword v57, v[16:17], off
	global_load_dword v58, v[18:19], off
	global_load_dword v59, v[4:5], off
	v_cvt_f32_ubyte0_e32 v4, v23
	v_mul_f32_e32 v4, v51, v4
	v_mul_f32_e32 v4, 0x3fb8aa3b, v4
	v_exp_f32_e32 v153, v4
	v_xor_b32_e32 v4, 15, v49
	v_cvt_f32_ubyte0_e32 v4, v4
	v_mul_f32_e32 v4, v51, v4
	v_mul_f32_e32 v4, 0x3fb8aa3b, v4
	v_exp_f32_e32 v154, v4
	v_xor_b32_e32 v4, 14, v49
	v_cvt_f32_ubyte0_e32 v4, v4
	v_mul_f32_e32 v4, v51, v4
	v_mul_f32_e32 v4, 0x3fb8aa3b, v4
	v_exp_f32_e32 v155, v4
	v_xor_b32_e32 v4, 13, v49
	v_cvt_f32_ubyte0_e32 v4, v4
	v_mul_f32_e32 v4, v51, v4
	v_xad_u32 v14, v174, -1, s55
	v_mul_f32_e32 v4, 0x3fb8aa3b, v4
	v_cndmask_b32_e32 v14, v14, v174, vcc
	v_exp_f32_e32 v156, v4
	v_add_u32_e32 v4, s56, v22
	v_add_u32_e32 v14, s56, v14
	v_and_b32_e32 v50, 0x78, v48
	v_ashrrev_i32_e32 v5, 31, v4
	v_ashrrev_i32_e32 v15, 31, v14
	v_lshlrev_b32_e32 v60, 1, v50
	v_lshlrev_b64 v[12:13], 13, v[4:5]
	v_lshlrev_b64 v[16:17], 13, v[14:15]
	v_or_b32_e32 v12, v12, v60
	v_or_b32_e32 v16, v16, v60
	v_lshl_add_u64 v[4:5], s[40:41], 0, v[12:13]
	v_lshl_add_u64 v[8:9], s[38:39], 0, v[12:13]
	v_lshl_add_u64 v[12:13], s[36:37], 0, v[12:13]
	v_lshl_add_u64 v[18:19], s[40:41], 0, v[16:17]
	global_load_dwordx4 v[4:7], v[4:5], off
	s_nop 0
	global_load_dwordx4 v[8:11], v[8:9], off
	s_nop 0
	global_load_dwordx4 v[12:15], v[12:13], off
	s_nop 0
	global_load_dwordx4 v[64:67], v[18:19], off
	v_lshl_add_u64 v[18:19], s[38:39], 0, v[16:17]
	v_lshl_add_u64 v[16:17], s[36:37], 0, v[16:17]
	global_load_dwordx4 v[68:71], v[18:19], off
	global_load_dwordx4 v[72:75], v[16:17], off
	v_xor_b32_e32 v16, 12, v49
	v_cvt_f32_ubyte0_e32 v16, v16
	v_mul_f32_e32 v16, v51, v16
	v_mul_f32_e32 v16, 0x3fb8aa3b, v16
	v_exp_f32_e32 v157, v16
	s_waitcnt vmcnt(37)
	v_cndmask_b32_e64 v16, v24, 0, s[0:1]
	v_bfe_u32 v1, v1, 2, 2
	v_or_b32_e32 v1, v49, v1
	v_and_b32_e32 v250, 7, v1
	v_lshrrev_b32_e32 v251, 3, v1
	v_mul_u32_u24_e32 v250, 0x120, v250
	v_mul_u32_u24_e32 v251, 0x910, v251
	v_add_u32_e32 v49, v250, v251
	v_and_b32_e32 v48, 24, v48
	v_ashrrev_i32_e32 v1, 31, v0
	v_add3_u32 v176, 0, v49, v48
	v_lshlrev_b32_e32 v48, 3, v3
	s_waitcnt vmcnt(29)
	v_cndmask_b32_e64 v24, v32, 0, s[0:1]
	v_and_b32_e32 v250, 7, v173
	v_lshrrev_b32_e32 v251, 3, v173
	v_mul_u32_u24_e32 v250, 0x120, v250
	v_mul_u32_u24_e32 v251, 0x910, v251
	v_add_u32_e32 v3, v250, v251
	v_lshl_add_u32 v177, v0, 1, v176
	v_lshl_add_u64 v[0:1], v[0:1], 1, s[46:47]
	v_mov_b32_e32 v49, v2
	s_mov_b32 s57, 3
	v_cndmask_b32_e64 v17, v25, 0, s[0:1]
	v_cndmask_b32_e64 v18, v26, 0, s[0:1]
	s_waitcnt vmcnt(21)
	v_cndmask_b32_e64 v32, v40, 0, s[0:1]
	v_cndmask_b32_e64 v19, v27, 0, s[0:1]
	v_cndmask_b32_e64 v20, v28, 0, s[0:1]
	v_cndmask_b32_e64 v21, v29, 0, s[0:1]
	v_cndmask_b32_e64 v22, v30, 0, s[0:1]
	v_cndmask_b32_e64 v23, v31, 0, s[0:1]
	v_cndmask_b32_e64 v25, v33, 0, s[0:1]
	v_cndmask_b32_e64 v26, v34, 0, s[0:1]
	v_cndmask_b32_e64 v27, v35, 0, s[0:1]
	s_waitcnt vmcnt(13)
	v_cndmask_b32_e64 v40, v52, 0, s[0:1]
	v_mul_f32_e32 v52, 0x42000000, v51
	v_mul_f32_e32 v52, 0x3fb8aa3b, v52
	v_exp_f32_e32 v158, v52
	v_add_u32_e32 v52, 17, v173
	v_cvt_f32_ubyte0_e32 v52, v52
	v_mul_f32_e32 v52, v51, v52
	v_mul_f32_e32 v52, 0x3fb8aa3b, v52
	v_exp_f32_e32 v160, v52
	v_add_u32_e32 v52, 1, v173
	v_cvt_f32_ubyte0_e32 v52, v52
	v_mul_f32_e32 v51, v51, v52
	v_mul_f32_e32 v51, 0x3fb8aa3b, v51
	v_exp_f32_e32 v162, v51
	v_and_b32_e32 v250, 7, v174
	v_lshrrev_b32_e32 v251, 3, v174
	v_mul_u32_u24_e32 v250, 0x120, v250
	v_mul_u32_u24_e32 v251, 0x910, v251
	v_add_u32_e32 v51, v250, v251
	v_cndmask_b32_e64 v28, v36, 0, s[0:1]
	v_cndmask_b32_e64 v29, v37, 0, s[0:1]
	v_cndmask_b32_e64 v30, v38, 0, s[0:1]
	v_cndmask_b32_e64 v31, v39, 0, s[0:1]
	v_cndmask_b32_e64 v33, v41, 0, s[0:1]
	v_cndmask_b32_e64 v34, v42, 0, s[0:1]
	v_cndmask_b32_e64 v35, v43, 0, s[0:1]
	v_cndmask_b32_e64 v36, v44, 0, s[0:1]
	v_cndmask_b32_e64 v37, v45, 0, s[0:1]
	v_cndmask_b32_e64 v38, v46, 0, s[0:1]
	v_cndmask_b32_e64 v39, v47, 0, s[0:1]
	s_waitcnt vmcnt(12)
	v_cndmask_b32_e64 v41, v53, 0, s[0:1]
	s_waitcnt vmcnt(11)
	v_cndmask_b32_e64 v42, v54, 0, s[0:1]
	s_waitcnt vmcnt(10)
	v_cndmask_b32_e64 v43, v55, 0, s[0:1]
	s_waitcnt vmcnt(9)
	v_cndmask_b32_e64 v44, v56, 0, s[0:1]
	s_waitcnt vmcnt(8)
	v_cndmask_b32_e64 v45, v57, 0, s[0:1]
	s_waitcnt vmcnt(7)
	v_cndmask_b32_e64 v46, v58, 0, s[0:1]
	s_waitcnt vmcnt(6)
	v_cndmask_b32_e64 v47, v59, 0, s[0:1]
	v_add3_u32 v175, 0, v60, v51
	s_add_i32 s0, s58, -1
	v_add3_u32 v178, 0, v48, v3
	v_add3_u32 v179, 0, v3, v48
	v_mov_b32_e32 v164, v158
	v_mov_b32_e32 v165, v158
	v_mov_b32_e32 v161, v160
	v_mov_b32_e32 v166, v160
	v_mov_b32_e32 v167, v160
	v_mov_b32_e32 v163, v162
	v_mov_b32_e32 v168, v162
	v_mov_b32_e32 v169, v162
	v_lshl_add_u64 v[170:171], v[0:1], 0, v[48:49]
	v_xad_u32 v180, v173, -1, s55
	v_lshlrev_b32_e32 v181, 1, v50
	v_readlane_b32 s77, v254, 1
	v_readlane_b32 s80, v254, 4
	v_readlane_b32 s81, v254, 5
	v_readlane_b32 s82, v254, 6
	v_readlane_b32 s83, v254, 7
	s_waitcnt vmcnt(0)
.LBB0_1370:
	s_add_i32 s1, s57, -1
	s_waitcnt vmcnt(7)
	ds_write_b128 v175, v[72:75]
	ds_write_b128 v175, v[68:71] offset:9280
	ds_write_b128 v175, v[64:67] offset:18560
	v_cndmask_b32_e32 v65, v180, v173, vcc
	v_xor_b32_e32 v66, 0xffffffef, v173
	v_xor_b32_e32 v70, 0xffffffcf, v173
	s_min_u32 s18, s1, s0
	v_add_u32_e32 v69, 48, v173
	v_xor_b32_e32 v67, 0xffffffdf, v173
	v_add_u32_e32 v71, s55, v66
	v_add_u32_e32 v66, s56, v65
	v_add_u32_e32 v70, s55, v70
	v_lshl_add_u32 v73, s18, 5, v174
	v_add_u32_e32 v64, 16, v173
	v_add_u32_e32 v68, 32, v173
	v_add_u32_e32 v65, s55, v67
	v_ashrrev_i32_e32 v67, 31, v66
	v_cndmask_b32_e32 v69, v70, v69, vcc
	v_xad_u32 v70, v73, -1, s55
	v_cndmask_b32_e32 v71, v71, v64, vcc
	v_cndmask_b32_e32 v68, v65, v68, vcc
	v_lshlrev_b64 v[64:65], 11, v[66:67]
	v_cndmask_b32_e32 v67, v70, v73, vcc
	s_min_u32 s42, s57, s0
	v_lshl_add_u64 v[242:243], v[170:171], 0, v[64:65]
	v_add_u32_e32 v64, s56, v67
	v_lshl_add_u32 v72, s42, 5, v174
	v_ashrrev_i32_e32 v65, 31, v64
	v_cvt_pk_bf16_f32 v60, v44, v45
	v_cvt_pk_bf16_f32 v61, v46, v47
	v_cvt_pk_bf16_f32 v62, v40, v41
	v_cvt_pk_bf16_f32 v63, v42, v43
	v_xad_u32 v74, v72, -1, s55
	v_lshlrev_b64 v[64:65], 13, v[64:65]
	v_cndmask_b32_e32 v66, v74, v72, vcc
	v_or_b32_e32 v64, v64, v181
	v_add_u32_e32 v238, s56, v68
	v_add_u32_e32 v240, s56, v69
	v_add_u32_e32 v244, s56, v66
	v_lshl_add_u64 v[66:67], s[36:37], 0, v[64:65]
	v_lshl_add_u64 v[68:69], s[38:39], 0, v[64:65]
	v_lshl_add_u64 v[64:65], s[40:41], 0, v[64:65]
	v_add_u32_e32 v0, 0x1000, v178
	v_add_u32_e32 v1, 0x2000, v179
	v_add_u32_e32 v182, 0x3000, v179
	v_add_u32_e32 v236, s56, v71
	global_load_dwordx4 v[72:75], v[66:67], off
	s_nop 0
	global_load_dwordx4 v[68:71], v[68:69], off
	s_nop 0
	global_load_dwordx4 v[64:67], v[64:65], off
	s_waitcnt lgkmcnt(0)
	s_barrier
	ds_read_b64 v[188:189], v178
	ds_read_b64 v[190:191], v178 offset:32
	ds_read_b64 v[192:193], v0 offset:544
	ds_read_b64 v[194:195], v0 offset:576
	ds_read_b64 v[196:197], v0 offset:608
	ds_read_b64 v[198:199], v0 offset:640
	ds_read_b64 v[200:201], v1 offset:1088
	ds_read_b64 v[202:203], v1 offset:1120
	ds_read_b64 v[204:205], v182 offset:1632
	ds_read_b64 v[206:207], v182 offset:1664
	ds_read_b64_tr_b16 v[210:211], v176 offset:13920
	ds_read_b64_tr_b16 v[212:213], v177 offset:18560
	ds_read_b64_tr_b16 v[214:215], v177 offset:23200
	ds_read_b64_tr_b16 v[208:209], v176 offset:9280
	ds_read_b64_tr_b16 v[216:217], v176 offset:9312
	ds_read_b64_tr_b16 v[220:221], v176 offset:9344
	ds_read_b64_tr_b16 v[222:223], v176 offset:13984
	ds_read_b64_tr_b16 v[218:219], v176 offset:13952
	ds_read_b64_tr_b16 v[230:231], v176 offset:9504
	s_waitcnt lgkmcnt(7)
	v_lshlrev_b32_e32 v232, 16, v212
	v_and_b32_e32 v233, 0xffff0000, v212
	v_lshlrev_b32_e32 v234, 16, v213
	v_and_b32_e32 v235, 0xffff0000, v213
	s_waitcnt lgkmcnt(6)
	v_lshlrev_b32_e32 v246, 16, v214
	v_and_b32_e32 v247, 0xffff0000, v214
	v_lshlrev_b32_e32 v248, 16, v215
	v_and_b32_e32 v249, 0xffff0000, v215
	v_mov_b32_e32 v159, v158
	v_mfma_f32_16x16x32_bf16 v[226:229], v[60:63], v[192:195], 0
	v_mul_f32_e64 v232, v150, v232
	v_mul_f32_e64 v233, v151, v233
	v_pk_mul_f32 v[234:235], v[152:153], v[234:235]
	v_pk_mul_f32 v[44:45], v[164:165], v[44:45]
	v_mfma_f32_16x16x32_bf16 v[60:63], v[60:63], v[188:191], 0
	v_mul_f32_e64 v46, v158, v46
	v_mul_f32_e64 v47, v159, v47
	v_pk_mul_f32 v[40:41], v[164:165], v[40:41]
	v_pk_mul_f32 v[42:43], v[158:159], v[42:43]
	v_mfma_f32_16x16x32_bf16 v[188:191], v[200:203], v[188:191], 0
	v_cvt_pk_bf16_f32 v52, v36, v37
	v_cvt_pk_bf16_f32 v53, v38, v39
	v_cvt_pk_bf16_f32 v54, v32, v33
	v_mfma_f32_16x16x32_bf16 v[200:203], v[200:203], v[192:195], 0
	v_cvt_pk_bf16_f32 v55, v34, v35
	v_cvt_pk_bf16_f32 v56, v28, v29
	v_cvt_pk_bf16_f32 v57, v30, v31
	v_mfma_f32_16x16x32_bf16 v[192:195], v[204:207], v[192:195], 0
	v_mul_f32_e64 v206, v154, v246
	v_mul_f32_e64 v207, v155, v247
	v_pk_mul_f32 v[246:247], v[156:157], v[248:249]
	v_cvt_pk_bf16_f32 v204, v232, v233
	v_cvt_pk_bf16_f32 v205, v234, v235
	v_cvt_pk_bf16_f32 v206, v206, v207
	v_cvt_pk_bf16_f32 v207, v246, v247
	v_pk_mul_f32 v[36:37], v[164:165], v[36:37]
	v_pk_mul_f32 v[32:33], v[164:165], v[32:33]
	s_waitcnt lgkmcnt(5)
	v_mfma_f32_16x16x32_bf16 v[44:47], v[208:211], v[204:207], v[44:47]
	ds_read_b64_tr_b16 v[210:211], v176 offset:14016
	ds_read_b64_tr_b16 v[208:209], v176 offset:9376
	ds_read_b64_tr_b16 v[232:233], v176 offset:9408
	v_pk_mul_f32 v[28:29], v[164:165], v[28:29]
	v_pk_mul_f32 v[38:39], v[158:159], v[38:39]
	s_waitcnt lgkmcnt(4)
	v_mfma_f32_16x16x32_bf16 v[40:43], v[216:219], v[204:207], v[40:43]
	ds_read_b64_tr_b16 v[216:217], v176 offset:9440
	ds_read_b64_tr_b16 v[234:235], v176 offset:14048
	ds_read_b64_tr_b16 v[218:219], v176 offset:14080
	v_pk_mul_f32 v[34:35], v[158:159], v[34:35]
	v_pk_mul_f32 v[30:31], v[158:159], v[30:31]
	v_mfma_f32_16x16x32_bf16 v[36:39], v[220:223], v[204:207], v[36:39]
	v_ashrrev_i32_e32 v245, 31, v244
	v_ashrrev_i32_e32 v237, 31, v236
	v_cvt_pk_bf16_f32 v58, v24, v25
	s_waitcnt lgkmcnt(4)
	v_mfma_f32_16x16x32_bf16 v[32:35], v[208:211], v[204:207], v[32:35]
	ds_read_b64_tr_b16 v[208:209], v176 offset:9472
	ds_read_b64_tr_b16 v[210:211], v176 offset:14112
	v_cvt_pk_bf16_f32 v59, v26, v27
	s_waitcnt lgkmcnt(3)
	v_mfma_f32_16x16x32_bf16 v[220:223], v[232:235], v[204:207], v[28:31]
	ds_read_b64_tr_b16 v[232:233], v176 offset:14144
	v_cvt_pk_bf16_f32 v48, v20, v21
	v_cvt_pk_bf16_f32 v49, v22, v23
	v_lshlrev_b64 v[28:29], 13, v[244:245]
	v_cvt_pk_bf16_f32 v50, v16, v17
	v_cvt_pk_bf16_f32 v51, v18, v19
	v_pk_mul_f32 v[24:25], v[164:165], v[24:25]
	v_pk_mul_f32 v[20:21], v[164:165], v[20:21]
	v_pk_mul_f32 v[16:17], v[164:165], v[16:17]
	v_pk_mul_f32 v[26:27], v[158:159], v[26:27]
	v_pk_mul_f32 v[22:23], v[158:159], v[22:23]
	v_pk_mul_f32 v[18:19], v[158:159], v[18:19]
	v_ashrrev_i32_e32 v239, 31, v238
	v_ashrrev_i32_e32 v241, 31, v240
	v_lshlrev_b64 v[236:237], 11, v[236:237]
	v_or_b32_e32 v28, v28, v181
	v_lshlrev_b64 v[246:247], 11, v[238:239]
	v_lshlrev_b64 v[248:249], 11, v[240:241]
	s_waitcnt lgkmcnt(3)
	v_mfma_f32_16x16x32_bf16 v[216:219], v[216:219], v[204:207], v[24:27]
	v_lshl_add_u64 v[234:235], v[170:171], 0, v[236:237]
	v_lshl_add_u64 v[236:237], s[36:37], 0, v[28:29]
	v_lshl_add_u64 v[238:239], s[38:39], 0, v[28:29]
	s_waitcnt lgkmcnt(1)
	v_mfma_f32_16x16x32_bf16 v[208:211], v[208:211], v[204:207], v[20:23]
	ds_read_b64 v[24:25], v1 offset:1152
	ds_read_b64 v[26:27], v1 offset:1184
	v_lshl_add_u64 v[240:241], s[40:41], 0, v[28:29]
	ds_read_b64 v[28:29], v182 offset:1696
	ds_read_b64 v[30:31], v182 offset:1728
	s_waitcnt lgkmcnt(4)
	v_mfma_f32_16x16x32_bf16 v[204:207], v[230:233], v[204:207], v[16:19]
	v_mov_b32_e32 v3, v2
	v_add_u32_e32 v183, 0x6000, v178
	v_add_u32_e32 v184, 0x7000, v178
	ds_read_b64 v[16:17], v178 offset:64
	ds_read_b64 v[18:19], v178 offset:96
	v_mfma_f32_16x16x32_bf16 v[226:229], v[52:55], v[196:199], v[226:229]
	v_add_u32_e32 v185, 0x8800, v179
	v_add_u32_e32 v186, 0x9800, v179
	s_add_i32 s57, s57, 2
	s_waitcnt lgkmcnt(0)
	v_mfma_f32_16x16x32_bf16 v[20:23], v[52:55], v[16:19], v[60:63]
	ds_read_b64 v[52:53], v0 offset:672
	ds_read_b64 v[54:55], v0 offset:704
	s_nop 1
	ds_read_b64 v[60:61], v178 offset:128
	ds_read_b64 v[62:63], v178 offset:160
	v_add_u32_e32 v173, 64, v173
	v_subrev_u32_e32 v180, 64, v180
	v_mfma_f32_16x16x32_bf16 v[16:19], v[24:27], v[16:19], v[188:191]
	s_cmp_ge_u32 s1, s58
	v_mfma_f32_16x16x32_bf16 v[24:27], v[24:27], v[196:199], v[200:203]
	v_mfma_f32_16x16x32_bf16 v[28:31], v[28:31], v[196:199], v[192:195]
	s_nop 2
	ds_read_b64 v[192:193], v1 offset:1216
	ds_read_b64 v[194:195], v1 offset:1248
	ds_read_b64 v[196:197], v178 offset:192
	ds_read_b64 v[198:199], v178 offset:224
	ds_read_b64 v[200:201], v0 offset:736
	ds_read_b64 v[202:203], v0 offset:768
	s_waitcnt lgkmcnt(8)
	v_mfma_f32_16x16x32_bf16 v[188:191], v[56:59], v[52:55], v[226:229]
	s_waitcnt lgkmcnt(6)
	v_mfma_f32_16x16x32_bf16 v[20:23], v[56:59], v[60:63], v[20:23]
	ds_read_b64 v[56:57], v182 offset:1760
	ds_read_b64 v[58:59], v182 offset:1792
	ds_read_b64 v[226:227], v1 offset:1280
	ds_read_b64 v[228:229], v1 offset:1312
	ds_read_b64 v[230:231], v182 offset:1824
	ds_read_b64 v[232:233], v182 offset:1856
	s_waitcnt vmcnt(5)
	ds_write_b128 v175, v[12:15] offset:27840
	ds_write_b128 v175, v[8:11] offset:37120
	ds_write_b128 v175, v[4:7] offset:46400
	s_waitcnt lgkmcnt(13)
	v_mfma_f32_16x16x32_bf16 v[16:19], v[192:195], v[60:63], v[16:19]
	v_mfma_f32_16x16x32_bf16 v[4:7], v[192:195], v[52:55], v[24:27]
	s_waitcnt lgkmcnt(7)
	v_mfma_f32_16x16x32_bf16 v[8:11], v[56:59], v[52:55], v[28:31]
	s_nop 0
	v_cvt_pk_bf16_f32 v24, v44, v45
	v_cvt_pk_bf16_f32 v25, v46, v47
	v_cvt_pk_bf16_f32 v26, v40, v41
	s_waitcnt lgkmcnt(5)
	v_mfma_f32_16x16x32_bf16 v[16:19], v[226:229], v[196:199], v[16:19]
	v_mul_f32_e64 v28, v164, v44
	v_mul_f32_e64 v29, v165, v45
	v_cvt_pk_bf16_f32 v27, v42, v43
	v_pk_mul_f32 v[30:31], v[158:159], v[46:47]
	v_mfma_f32_16x16x32_bf16 v[4:7], v[226:229], v[200:203], v[4:7]
	v_cvt_pk_bf16_f32 v52, v36, v37
	s_nop 1
	v_pk_mul_f32 v[18:19], v[146:147], v[18:19]
	v_pk_mul_f32 v[0:1], v[142:143], v[16:17]
	s_waitcnt lgkmcnt(3)
	v_mfma_f32_16x16x32_bf16 v[8:11], v[230:233], v[200:203], v[8:11]
	v_cvt_pk_bf16_f32 v0, v0, v1
	v_pk_mul_f32 v[6:7], v[148:149], v[6:7]
	v_pk_mul_f32 v[4:5], v[144:145], v[4:5]
	v_cvt_pk_bf16_f32 v1, v18, v19
	v_cvt_pk_bf16_f32 v4, v4, v5
	s_nop 2
	v_pk_mul_f32 v[16:17], v[146:147], v[10:11]
	v_pk_mul_f32 v[44:45], v[142:143], v[8:9]
	v_cvt_pk_bf16_f32 v5, v6, v7
	v_cvt_pk_bf16_f32 v6, v44, v45
	v_cvt_pk_bf16_f32 v7, v16, v17
	v_mfma_f32_16x16x32_bf16 v[12:15], v[48:51], v[200:203], v[188:191]
	v_cvt_pk_bf16_f32 v53, v38, v39
	v_pk_mul_f32 v[38:39], v[158:159], v[38:39]
	v_pk_mul_f32 v[36:37], v[164:165], v[36:37]
	v_mfma_f32_16x16x32_bf16 v[20:23], v[48:51], v[196:199], v[20:23]
	v_cvt_pk_bf16_f32 v54, v32, v33
	v_cvt_pk_bf16_f32 v55, v34, v35
	v_pk_mul_f32 v[42:43], v[158:159], v[42:43]
	v_mfma_f32_16x16x32_bf16 v[8:11], v[212:215], v[0:3], 0
	v_mul_f32_e64 v40, v164, v40
	v_mul_f32_e64 v41, v165, v41
	v_pk_mul_f32 v[34:35], v[158:159], v[34:35]
	v_pk_mul_f32 v[32:33], v[164:165], v[32:33]
	v_mfma_f32_16x16x32_bf16 v[4:7], v[212:215], v[4:7], 0
	v_mul_f32_e64 v50, v158, v222
	v_mul_f32_e64 v51, v159, v223
	s_nop 0
	v_pk_fma_f32 v[8:9], v[162:163], v[20:21], v[8:9]
	v_pk_mul_f32 v[48:49], v[164:165], v[220:221]
	v_cvt_pk_bf16_f32 v8, v8, v9
	v_cvt_pk_bf16_f32 v56, v220, v221
	s_nop 0
	v_pk_fma_f32 v[0:1], v[166:167], v[14:15], v[6:7]
	v_pk_fma_f32 v[6:7], v[168:169], v[22:23], v[10:11]
	v_pk_fma_f32 v[4:5], v[160:161], v[12:13], v[4:5]
	v_cvt_pk_bf16_f32 v9, v6, v7
	v_cvt_pk_bf16_f32 v4, v4, v5
	v_cvt_pk_bf16_f32 v5, v0, v1
	global_store_dwordx2 v[242:243], v[8:9], off
	global_store_dwordx2 v[234:235], v[4:5], off
	global_load_dwordx4 v[12:15], v[236:237], off
	s_nop 0
	global_load_dwordx4 v[8:11], v[238:239], off
	global_load_dwordx4 v[4:7], v[240:241], off
	s_waitcnt lgkmcnt(0)
	s_barrier
	ds_read_b64 v[16:17], v183 offset:3264
	ds_read_b64 v[18:19], v183 offset:3296
	ds_read_b64 v[20:21], v184 offset:3808
	ds_read_b64 v[22:23], v184 offset:3840
	ds_read_b64 v[60:61], v184 offset:3872
	ds_read_b64 v[62:63], v184 offset:3904
	ds_read_b64 v[44:45], v185 offset:2304
	ds_read_b64 v[46:47], v185 offset:2336
	ds_read_b64 v[188:189], v186 offset:2848
	ds_read_b64 v[190:191], v186 offset:2880
	ds_read_b64_tr_b16 v[194:195], v176 offset:41760
	ds_read_b64_tr_b16 v[196:197], v177 offset:46400
	ds_read_b64_tr_b16 v[198:199], v177 offset:51040
	ds_read_b64_tr_b16 v[192:193], v176 offset:37120
	ds_read_b64_tr_b16 v[200:201], v176 offset:37152
	ds_read_b64_tr_b16 v[212:213], v176 offset:37184
	ds_read_b64_tr_b16 v[214:215], v176 offset:41824
	s_waitcnt lgkmcnt(13)
	v_mfma_f32_16x16x32_bf16 v[226:229], v[24:27], v[20:23], 0
	s_waitcnt lgkmcnt(5)
	v_lshlrev_b32_e32 v0, 16, v196
	v_and_b32_e32 v1, 0xffff0000, v196
	v_pk_mul_f32 v[0:1], v[150:151], v[0:1]
	v_mfma_f32_16x16x32_bf16 v[234:237], v[24:27], v[16:19], 0
	v_lshlrev_b32_e32 v24, 16, v197
	v_and_b32_e32 v25, 0xffff0000, v197
	v_pk_mul_f32 v[24:25], v[152:153], v[24:25]
	v_mfma_f32_16x16x32_bf16 v[238:241], v[44:47], v[16:19], 0
	s_waitcnt lgkmcnt(4)
	v_lshlrev_b32_e32 v16, 16, v198
	v_and_b32_e32 v17, 0xffff0000, v198
	v_lshlrev_b32_e32 v18, 16, v199
	v_and_b32_e32 v19, 0xffff0000, v199
	v_mfma_f32_16x16x32_bf16 v[242:245], v[44:47], v[20:23], 0
	ds_read_b64_tr_b16 v[202:203], v176 offset:41792
	ds_read_b64_tr_b16 v[230:231], v176 offset:37344
	v_cvt_pk_bf16_f32 v57, v222, v223
	v_cvt_pk_bf16_f32 v58, v216, v217
	v_mfma_f32_16x16x32_bf16 v[188:191], v[188:191], v[20:23], 0
	v_mul_f32_e64 v20, v154, v16
	v_mul_f32_e64 v21, v155, v17
	v_pk_mul_f32 v[22:23], v[156:157], v[18:19]
	v_cvt_pk_bf16_f32 v16, v0, v1
	v_cvt_pk_bf16_f32 v17, v24, v25
	v_cvt_pk_bf16_f32 v18, v20, v21
	v_cvt_pk_bf16_f32 v19, v22, v23
	ds_read_b64_tr_b16 v[22:23], v176 offset:41856
	ds_read_b64_tr_b16 v[20:21], v176 offset:37216
	ds_read_b64_tr_b16 v[24:25], v176 offset:37248
	s_waitcnt lgkmcnt(8)
	v_mfma_f32_16x16x32_bf16 v[44:47], v[192:195], v[16:19], v[28:31]
	ds_read_b64_tr_b16 v[192:193], v176 offset:37280
	ds_read_b64_tr_b16 v[26:27], v176 offset:41888
	ds_read_b64_tr_b16 v[194:195], v176 offset:41920
	ds_read_b64_tr_b16 v[232:233], v176 offset:41984
	v_cvt_pk_bf16_f32 v59, v218, v219
	s_waitcnt lgkmcnt(9)
	v_mfma_f32_16x16x32_bf16 v[36:39], v[212:215], v[16:19], v[36:39]
	ds_read_b64_tr_b16 v[212:213], v176 offset:37312
	ds_read_b64_tr_b16 v[214:215], v176 offset:41952
	s_waitcnt lgkmcnt(10)
	v_mfma_f32_16x16x32_bf16 v[40:43], v[200:203], v[16:19], v[40:43]
	v_mul_f32_e64 v202, v158, v218
	v_mul_f32_e64 v203, v159, v219
	v_pk_mul_f32 v[200:201], v[164:165], v[216:217]
	ds_read_b64 v[216:217], v183 offset:3392
	ds_read_b64 v[218:219], v183 offset:3424
	s_waitcnt lgkmcnt(9)
	v_mfma_f32_16x16x32_bf16 v[32:35], v[20:23], v[16:19], v[32:35]
	v_mul_f32_e64 v22, v158, v210
	v_mul_f32_e64 v23, v159, v211
	v_pk_mul_f32 v[20:21], v[164:165], v[208:209]
	s_waitcnt lgkmcnt(6)
	v_mfma_f32_16x16x32_bf16 v[28:31], v[24:27], v[16:19], v[48:51]
	s_waitcnt lgkmcnt(5)
	v_mfma_f32_16x16x32_bf16 v[24:27], v[192:195], v[16:19], v[200:203]
	ds_read_b64 v[192:193], v185 offset:2368
	ds_read_b64 v[194:195], v185 offset:2400
	v_pk_mul_f32 v[50:51], v[158:159], v[206:207]
	v_pk_mul_f32 v[48:49], v[164:165], v[204:205]
	s_waitcnt lgkmcnt(4)
	v_mfma_f32_16x16x32_bf16 v[20:23], v[212:215], v[16:19], v[20:23]
	ds_read_b64 v[212:213], v186 offset:2912
	ds_read_b64 v[214:215], v186 offset:2944
	v_cvt_pk_bf16_f32 v202, v204, v205
	v_cvt_pk_bf16_f32 v203, v206, v207
	v_mfma_f32_16x16x32_bf16 v[16:19], v[230:233], v[16:19], v[48:51]
	ds_read_b64 v[204:205], v183 offset:3456
	ds_read_b64 v[206:207], v183 offset:3488
	v_cvt_pk_bf16_f32 v200, v208, v209
	v_cvt_pk_bf16_f32 v201, v210, v211
	ds_read_b64 v[48:49], v183 offset:3328
	ds_read_b64 v[50:51], v183 offset:3360
	v_mfma_f32_16x16x32_bf16 v[226:229], v[52:55], v[60:63], v[226:229]
	s_waitcnt lgkmcnt(0)
	v_mfma_f32_16x16x32_bf16 v[52:55], v[52:55], v[48:51], v[234:237]
	v_mfma_f32_16x16x32_bf16 v[48:51], v[192:195], v[48:51], v[238:241]
	v_mfma_f32_16x16x32_bf16 v[192:195], v[192:195], v[60:63], v[242:245]
	v_mfma_f32_16x16x32_bf16 v[60:63], v[212:215], v[60:63], v[188:191]
	s_nop 2
	ds_read_b64 v[188:189], v184 offset:3936
	ds_read_b64 v[190:191], v184 offset:3968
	s_waitcnt lgkmcnt(0)
	v_mfma_f32_16x16x32_bf16 v[212:215], v[56:59], v[188:191], v[226:229]
	v_mfma_f32_16x16x32_bf16 v[52:55], v[56:59], v[216:219], v[52:55]
	ds_read_b64 v[56:57], v185 offset:2432
	ds_read_b64 v[58:59], v185 offset:2464
	s_waitcnt lgkmcnt(0)
	v_mfma_f32_16x16x32_bf16 v[48:51], v[56:59], v[216:219], v[48:51]
	v_mfma_f32_16x16x32_bf16 v[56:59], v[56:59], v[188:191], v[192:195]
	s_nop 2
	ds_read_b64 v[192:193], v186 offset:2976
	ds_read_b64 v[194:195], v186 offset:3008
	s_waitcnt lgkmcnt(0)
	v_mfma_f32_16x16x32_bf16 v[60:63], v[192:195], v[188:191], v[60:63]
	ds_read_b64 v[188:189], v184 offset:4000
	ds_read_b64 v[190:191], v184 offset:4032
	ds_read_b64 v[182:183], v185 offset:2496
	ds_read_b64 v[184:185], v185 offset:2528
	s_waitcnt lgkmcnt(0)
	v_mfma_f32_16x16x32_bf16 v[48:51], v[182:185], v[204:207], v[48:51]
	s_nop 7
	v_pk_mul_f32 v[50:51], v[146:147], v[50:51]
	v_mfma_f32_16x16x32_bf16 v[56:59], v[182:185], v[188:191], v[56:59]
	ds_read_b64 v[182:183], v186 offset:3040
	ds_read_b64 v[184:185], v186 offset:3072
	v_pk_mul_f32 v[0:1], v[142:143], v[48:49]
	s_waitcnt lgkmcnt(0)
	v_mfma_f32_16x16x32_bf16 v[60:63], v[182:185], v[188:191], v[60:63]
	s_nop 3
	v_mul_f32_e64 v182, v148, v58
	v_mul_f32_e64 v183, v149, v59
	v_pk_mul_f32 v[48:49], v[144:145], v[56:57]
	v_cvt_pk_bf16_f32 v0, v0, v1
	v_pk_mul_f32 v[62:63], v[146:147], v[62:63]
	v_pk_mul_f32 v[60:61], v[142:143], v[60:61]
	v_cvt_pk_bf16_f32 v1, v50, v51
	v_cvt_pk_bf16_f32 v48, v48, v49
	v_cvt_pk_bf16_f32 v49, v182, v183
	v_cvt_pk_bf16_f32 v50, v60, v61
	v_cvt_pk_bf16_f32 v51, v62, v63
	v_mfma_f32_16x16x32_bf16 v[192:195], v[200:203], v[188:191], v[212:215]
	v_mfma_f32_16x16x32_bf16 v[52:55], v[200:203], v[204:207], v[52:55]
	v_lshl_add_u64 v[200:201], v[170:171], 0, v[246:247]
	v_lshl_add_u64 v[202:203], v[170:171], 0, v[248:249]
	v_mfma_f32_16x16x32_bf16 v[56:59], v[196:199], v[0:3], 0
	v_mfma_f32_16x16x32_bf16 v[48:51], v[196:199], v[48:51], 0
	s_nop 6
	v_fma_f32 v52, v162, v52, v56
	v_fma_f32 v53, v163, v53, v57
	v_pk_fma_f32 v[0:1], v[166:167], v[194:195], v[50:51]
	v_pk_fma_f32 v[50:51], v[168:169], v[54:55], v[58:59]
	v_pk_fma_f32 v[48:49], v[160:161], v[192:193], v[48:49]
	v_cvt_pk_bf16_f32 v52, v52, v53
	v_cvt_pk_bf16_f32 v53, v50, v51
	v_cvt_pk_bf16_f32 v48, v48, v49
	v_cvt_pk_bf16_f32 v49, v0, v1
	global_store_dwordx2 v[200:201], v[52:53], off
	global_store_dwordx2 v[202:203], v[48:49], off
	s_cbranch_scc0 .LBB0_1370
	s_andn2_b64 vcc, exec, s[6:7]
	s_cbranch_vccnz .LBB0_1354
	s_add_u32 s0, s28, s14
	s_addc_u32 s1, s29, s15
	v_lshl_add_u64 v[0:1], v[112:113], 2, s[0:1]
	s_waitcnt vmcnt(2)
	v_lshl_add_u64 v[4:5], v[0:1], 0, v[76:77]
	global_store_dword v[4:5], v44, off nt
	v_lshl_add_u64 v[4:5], v[0:1], 0, v[78:79]
	global_store_dword v[4:5], v45, off nt
	v_lshl_add_u64 v[4:5], v[0:1], 0, v[80:81]
	global_store_dword v[4:5], v46, off nt
	v_lshl_add_u64 v[4:5], v[0:1], 0, v[82:83]
	global_store_dword v[4:5], v47, off nt
	v_lshl_add_u64 v[4:5], v[0:1], 0, v[84:85]
	global_store_dword v[4:5], v40, off nt
	v_lshl_add_u64 v[4:5], v[0:1], 0, v[86:87]
	global_store_dword v[4:5], v41, off nt
	v_lshl_add_u64 v[4:5], v[0:1], 0, v[88:89]
	global_store_dword v[4:5], v42, off nt
	v_lshl_add_u64 v[4:5], v[0:1], 0, v[90:91]
	global_store_dword v[4:5], v43, off nt
	v_lshl_add_u64 v[4:5], v[0:1], 0, v[92:93]
	global_store_dword v[4:5], v36, off nt
	v_lshl_add_u64 v[4:5], v[0:1], 0, v[94:95]
	global_store_dword v[4:5], v37, off nt
	v_lshl_add_u64 v[4:5], v[0:1], 0, v[96:97]
	global_store_dword v[4:5], v38, off nt
	v_lshl_add_u64 v[4:5], v[0:1], 0, v[98:99]
	global_store_dword v[4:5], v39, off nt
	v_lshl_add_u64 v[4:5], v[0:1], 0, v[100:101]
	global_store_dword v[4:5], v32, off nt
	v_lshl_add_u64 v[4:5], v[0:1], 0, v[102:103]
	global_store_dword v[4:5], v33, off nt
	v_lshl_add_u64 v[4:5], v[0:1], 0, v[104:105]
	global_store_dword v[4:5], v34, off nt
	v_lshl_add_u64 v[4:5], v[0:1], 0, v[106:107]
	global_store_dword v[4:5], v35, off nt
	v_lshl_add_u64 v[4:5], v[0:1], 0, v[108:109]
	global_store_dword v[4:5], v28, off nt
	v_lshl_add_u64 v[4:5], v[0:1], 0, v[110:111]
	global_store_dword v[4:5], v29, off nt
	v_lshl_add_u64 v[4:5], v[0:1], 0, v[138:139]
	global_store_dword v[4:5], v30, off nt
	v_lshl_add_u64 v[4:5], v[0:1], 0, v[136:137]
	global_store_dword v[4:5], v31, off nt
	v_lshl_add_u64 v[4:5], v[0:1], 0, v[134:135]
	global_store_dword v[4:5], v24, off nt
	v_lshl_add_u64 v[4:5], v[0:1], 0, v[132:133]
	global_store_dword v[4:5], v25, off nt
	v_lshl_add_u64 v[4:5], v[0:1], 0, v[130:131]
	global_store_dword v[4:5], v26, off nt
	v_lshl_add_u64 v[4:5], v[0:1], 0, v[128:129]
	global_store_dword v[4:5], v27, off nt
	v_lshl_add_u64 v[4:5], v[0:1], 0, v[126:127]
	global_store_dword v[4:5], v20, off nt
	v_lshl_add_u64 v[4:5], v[0:1], 0, v[124:125]
	global_store_dword v[4:5], v21, off nt
	v_lshl_add_u64 v[4:5], v[0:1], 0, v[122:123]
	global_store_dword v[4:5], v22, off nt
	v_lshl_add_u64 v[4:5], v[0:1], 0, v[120:121]
	global_store_dword v[4:5], v23, off nt
	v_lshl_add_u64 v[4:5], v[0:1], 0, v[118:119]
	global_store_dword v[4:5], v16, off nt
	v_lshl_add_u64 v[4:5], v[0:1], 0, v[116:117]
	global_store_dword v[4:5], v17, off nt
	v_lshl_add_u64 v[4:5], v[0:1], 0, v[114:115]
	v_lshl_add_u64 v[0:1], v[0:1], 0, v[140:141]
	global_store_dword v[4:5], v18, off nt
	global_store_dword v[0:1], v19, off nt
	s_branch .LBB0_1354
